# v8 + LayerNorm phases: ln_g/ln_b vectors preloaded once into registers (were reloaded 16x per iteration behind vmcnt(0)); per-chunk vmcnt(0) waits removed
# speedup vs baseline: 1.0192x; 1.0192x over previous
; template <int NR>
; __device__ __forceinline__ void ln_rows(const _Float16* z, bf16* xb, float* st, float* outf, int m0, int stride, const float* g, const float* b, int lane, bool final_out) {
;     typedef _Float16 h16x4 __attribute__((ext_vector_type(4)));
;     f32x4 v[NR][4]; float s[NR];
; #pragma unroll
;     for (int r = 0; r < NR; ++r) { const h16x4* zr = (const h16x4*)(z + (size_t)(m0 + r * stride) * D) + lane; s[r] = 0.f;
; #pragma unroll
;         for (int j = 0; j < 4; ++j) v[r][j] = __builtin_convertvector(zr[64 * j], f32x4); }
; #pragma unroll
;     for (int r = 0; r < NR; ++r)
; #pragma unroll
;         for (int j = 0; j < 4; ++j) s[r] += (v[r][j].x + v[r][j].y) + (v[r][j].z + v[r][j].w);
; #pragma unroll
;     for (int o = 1; o < 64; o <<= 1)
; #pragma unroll
;         for (int r = 0; r < NR; ++r) s[r] += __shfl_xor(s[r], o);
;     float mean[NR], s2[NR];
; #pragma unroll
;     for (int r = 0; r < NR; ++r) { mean[r] = s[r] * (1.f / D); s2[r] = 0.f;
; #pragma unroll
;         for (int j = 0; j < 4; ++j) { v[r][j] = v[r][j] - mean[r]; s2[r] += (v[r][j].x * v[r][j].x + v[r][j].y * v[r][j].y) + (v[r][j].z * v[r][j].z + v[r][j].w * v[r][j].w); } }
; #pragma unroll
;     for (int o = 1; o < 64; o <<= 1)
; #pragma unroll
;         for (int r = 0; r < NR; ++r) s2[r] += __shfl_xor(s2[r], o);
; #pragma unroll
;     for (int r = 0; r < NR; ++r) { const int m = m0 + r * stride; const float rstd = 1.f / sqrtf(s2[r] * (1.f / D) + LN_EPS);
;         if (!final_out && lane == 0) *(f32x2*)(st + 2 * (size_t)m) = (f32x2){mean[r], rstd};
; __global__ void __launch_bounds__(NTHR, 2) fwd_kernel(Params p) {
;     ...
;         } else if (PHON(2) && (k == 2 || k == 9 || k == 12)) {
;             const int li = (k == 2) ? 0 : (k == 9 ? 1 : 2);
;             const float* gg = p.ln_g + (size_t)(L * 3 + li) * D; const float* bb = p.ln_b + (size_t)(L * 3 + li) * D;
;             const bool wbf = !(L == 1 && k == 12);
;             { int m = gw;
;               for (; m + 3 * ngw < T; m += 4 * ngw) ln_rows<4>((const _Float16*)(ws_ + WS_Z16), XB, (float*)(ws_ + WS_STATS), p.out, m, ngw, gg, bb, lane, !wbf);
;               for (; m < T; m += ngw) ln_rows<1>((const _Float16*)(ws_ + WS_Z16), XB, (float*)(ws_ + WS_STATS), p.out, m, ngw, gg, bb, lane, !wbf); }
.LBB0_627:
	s_nop 0
	v_readlane_b32 s0, v254, 51
	v_readlane_b32 s1, v254, 52
	s_and_b64 vcc, exec, s[0:1]
	s_cbranch_vccz .LBB0_765
	v_readlane_b32 s0, v254, 50
	s_cmp_eq_u32 s0, 12
	v_readlane_b32 s0, v254, 45
	s_mul_i32 s0, s0, 3
	v_readlane_b32 s1, v254, 53
	s_cselect_b64 s[6:7], -1, 0
	s_add_i32 s0, s1, s0
	s_ashr_i32 s1, s0, 31
	v_readlane_b32 s16, v253, 56
	s_lshl_b64 s[0:1], s[0:1], 12
	v_readlane_b32 s26, v254, 2
	v_readlane_b32 s27, v254, 3
	s_add_u32 s12, s26, s0
	v_readlane_b32 s28, v254, 4
	s_addc_u32 s13, s27, s1
	v_readlane_b32 s29, v254, 5
	s_add_u32 s38, s28, s0
	v_readlane_b32 s0, v254, 40
	s_addc_u32 s39, s29, s1
	s_add_i32 s0, s0, -14
	s_cmp_lt_u32 s0, 13
	s_cselect_b64 s[0:1], -1, 0
	s_and_b64 s[0:1], s[0:1], s[6:7]
	s_mul_i32 s15, s94, 24
	s_xor_b64 s[8:9], s[0:1], -1
	s_add_i32 s0, s36, s15
	s_cmpk_gt_i32 s0, 0x7fff
	v_cmp_eq_u32_e32 vcc, 0, v162
	s_waitcnt vmcnt(0)
	v_lshlrev_b32_e32 v6, 4, v162
	s_mov_b32 s4, s36
	v_readlane_b32 s17, v253, 57
	v_readlane_b32 s18, v253, 58
	v_readlane_b32 s19, v253, 59
	v_readlane_b32 s20, v253, 60
	v_readlane_b32 s21, v253, 61
	v_readlane_b32 s22, v253, 62
	v_readlane_b32 s23, v253, 63
	v_readlane_b32 s24, v254, 0
	v_readlane_b32 s25, v254, 1
	v_readlane_b32 s30, v254, 6
	v_readlane_b32 s31, v254, 7
	s_cbranch_scc1 .LBB0_703
	v_readlane_b32 s0, v254, 43
	v_readlane_b32 s1, v254, 44
	s_add_u32 s56, s0, 0x40000
	v_lshlrev_b32_e32 v2, 3, v162
	v_mov_b32_e32 v3, v0
	s_addc_u32 s57, s1, 0
	v_lshl_add_u64 v[4:5], s[0:1], 0, v[2:3]
	s_mov_b64 s[0:1], 0x1b200000
	v_and_b32_e32 v1, 64, v231
	v_lshl_add_u64 v[8:9], v[4:5], 0, s[0:1]
	v_add_u32_e32 v4, 64, v1
	v_xor_b32_e32 v1, 1, v231
	v_cmp_lt_i32_e64 s[0:1], v1, v4
	v_xor_b32_e32 v5, 2, v231
	v_readlane_b32 s16, v253, 56
	v_cndmask_b32_e64 v1, v231, v1, s[0:1]
	v_cmp_lt_i32_e64 s[0:1], v5, v4
	v_mov_b32_e32 v7, v0
	v_readlane_b32 s30, v254, 6
	v_cndmask_b32_e64 v5, v231, v5, s[0:1]
	v_lshlrev_b32_e32 v86, 2, v5
	v_xor_b32_e32 v5, 4, v231
	v_cmp_lt_i32_e64 s[0:1], v5, v4
	v_readlane_b32 s31, v254, 7
	v_lshlrev_b32_e32 v1, 2, v1
	v_cndmask_b32_e64 v5, v231, v5, s[0:1]
	v_lshlrev_b32_e32 v87, 2, v5
	v_xor_b32_e32 v5, 8, v231
	v_cmp_lt_i32_e64 s[0:1], v5, v4
	s_and_b64 s[40:41], s[8:9], vcc
	v_lshl_add_u64 v[10:11], s[34:35], 0, v[2:3]
	v_cndmask_b32_e64 v5, v231, v5, s[0:1]
	v_lshlrev_b32_e32 v88, 2, v5
	v_xor_b32_e32 v5, 16, v231
	v_cmp_lt_i32_e64 s[0:1], v5, v4
	v_lshl_add_u64 v[12:13], s[12:13], 0, v[6:7]
	v_lshl_add_u64 v[14:15], s[38:39], 0, v[6:7]
	v_cndmask_b32_e64 v5, v231, v5, s[0:1]
	v_lshlrev_b32_e32 v89, 2, v5
	v_xor_b32_e32 v5, 32, v231
	v_cmp_lt_i32_e64 s[0:1], v5, v4
	v_lshl_add_u64 v[16:17], s[30:31], 0, v[6:7]
	s_lshl_b32 s58, s94, 4
	v_cndmask_b32_e64 v4, v231, v5, s[0:1]
	v_lshlrev_b32_e32 v90, 2, v4
	s_mov_b32 s4, s36
	s_mov_b32 s2, 0xf800000
	v_readlane_b32 s17, v253, 57
	v_readlane_b32 s18, v253, 58
	v_readlane_b32 s19, v253, 59
	v_readlane_b32 s20, v253, 60
	v_readlane_b32 s21, v253, 61
	v_readlane_b32 s22, v253, 62
	v_readlane_b32 s23, v253, 63
	v_readlane_b32 s24, v254, 0
	v_readlane_b32 s25, v254, 1
	v_readlane_b32 s26, v254, 2
	v_readlane_b32 s27, v254, 3
	v_readlane_b32 s28, v254, 4
	v_readlane_b32 s29, v254, 5
	global_load_dwordx4 v[116:119], v[12:13], off
	global_load_dwordx4 v[120:123], v[12:13], off offset:1024
	global_load_dwordx4 v[124:127], v[12:13], off offset:2048
	global_load_dwordx4 v[128:131], v[12:13], off offset:3072
	global_load_dwordx4 v[132:135], v[14:15], off
	global_load_dwordx4 v[136:139], v[14:15], off offset:1024
	global_load_dwordx4 v[140:143], v[14:15], off offset:2048
	global_load_dwordx4 v[144:147], v[14:15], off offset:3072
	s_branch .LBB0_631

; __device__ __forceinline__ unsigned pk2(float lo, float hi) { return f2bf(lo) | (f2bf(hi) << 16); }
; template <int NR>
; __device__ __forceinline__ void ln_rows(const _Float16* z, bf16* xb, float* st, float* outf, int m0, int stride, const float* g, const float* b, int lane, bool final_out) {
;     ...
;     for (int r = 0; r < NR; ++r) { const int m = m0 + r * stride; const float rstd = 1.f / sqrtf(s2[r] * (1.f / D) + LN_EPS);
;         if (!final_out && lane == 0) *(f32x2*)(st + 2 * (size_t)m) = (f32x2){mean[r], rstd};
;         f32x4* xr = (f32x4*)(outf + (size_t)m * D) + lane; unsigned long long* o8 = (unsigned long long*)(xb + (size_t)m * D) + lane;
; #pragma unroll
;         for (int j = 0; j < 4; ++j) { const f32x4 gg = ((const f32x4*)g)[lane + 64 * j], bb = ((const f32x4*)b)[lane + 64 * j];
;             const f32x4 y = v[r][j] * rstd * gg + bb;
;             if (final_out) xr[64 * j] = y;
;             else o8[64 * j] = (unsigned long long)pk2(y.x, y.y) | ((unsigned long long)pk2(y.z, y.w) << 32); } }
.LBB0_633:
	s_or_b64 exec, exec, s[0:1]
	s_nop 1
	v_mov_b64_e32 v[2:3], v[116:117]
	v_mov_b64_e32 v[4:5], v[118:119]
	v_mov_b64_e32 v[100:101], v[132:133]
	v_mov_b64_e32 v[102:103], v[134:135]
	v_pk_mul_f32 v[78:79], v[78:79], v[84:85] op_sel_hi:[1,0]
	v_pk_mul_f32 v[80:81], v[80:81], v[84:85] op_sel_hi:[1,0]
	v_lshl_add_u64 v[82:83], v[10:11], 0, s[54:55]
	s_mov_b64 s[0:1], -1
	s_and_b64 vcc, exec, s[8:9]
	v_pk_fma_f32 v[4:5], v[78:79], v[4:5], v[102:103]
	v_pk_fma_f32 v[2:3], v[80:81], v[2:3], v[100:101]
	s_cbranch_vccz .LBB0_635
	v_bfe_u32 v78, v2, 16, 1
	v_add3_u32 v78, v2, v78, s33
	v_bfe_u32 v79, v3, 16, 1
	v_lshrrev_b32_e32 v78, 16, v78
	v_add3_u32 v79, v3, v79, s33
	v_and_or_b32 v78, v79, s11, v78
	v_bfe_u32 v79, v4, 16, 1
	v_add3_u32 v79, v4, v79, s33
	v_bfe_u32 v80, v5, 16, 1
	v_lshrrev_b32_e32 v79, 16, v79
	v_add3_u32 v80, v5, v80, s33
	v_and_or_b32 v79, v80, s11, v79
	flat_store_dwordx2 v[82:83], v[78:79]
	s_mov_b64 s[0:1], 0

; __device__ __forceinline__ unsigned pk2(float lo, float hi) { return f2bf(lo) | (f2bf(hi) << 16); }
; template <int NR>
; __device__ __forceinline__ void ln_rows(const _Float16* z, bf16* xb, float* st, float* outf, int m0, int stride, const float* g, const float* b, int lane, bool final_out) {
;     ...
;     for (int r = 0; r < NR; ++r) { const int m = m0 + r * stride; const float rstd = 1.f / sqrtf(s2[r] * (1.f / D) + LN_EPS);
;         if (!final_out && lane == 0) *(f32x2*)(st + 2 * (size_t)m) = (f32x2){mean[r], rstd};
;         f32x4* xr = (f32x4*)(outf + (size_t)m * D) + lane; unsigned long long* o8 = (unsigned long long*)(xb + (size_t)m * D) + lane;
; #pragma unroll
;         for (int j = 0; j < 4; ++j) { const f32x4 gg = ((const f32x4*)g)[lane + 64 * j], bb = ((const f32x4*)b)[lane + 64 * j];
;             const f32x4 y = v[r][j] * rstd * gg + bb;
;             if (final_out) xr[64 * j] = y;
;             else o8[64 * j] = (unsigned long long)pk2(y.x, y.y) | ((unsigned long long)pk2(y.z, y.w) << 32); } }
.LBB0_637:
	s_nop 1
	v_mov_b64_e32 v[2:3], v[120:121]
	v_mov_b64_e32 v[4:5], v[122:123]
	s_nop 0
	v_mov_b64_e32 v[100:101], v[136:137]
	v_mov_b64_e32 v[102:103], v[138:139]
	v_mov_b32_e32 v80, v84
	v_mov_b32_e32 v81, v84
	v_mov_b32_e32 v85, v84
	v_pk_mul_f32 v[74:75], v[74:75], v[80:81]
	v_pk_mul_f32 v[76:77], v[76:77], v[84:85]
	s_mov_b64 s[4:5], -1
	s_andn2_b64 vcc, exec, s[8:9]
	v_pk_fma_f32 v[4:5], v[74:75], v[4:5], v[102:103]
	v_cndmask_b32_e64 v74, 0, 1, s[8:9]
	v_pk_fma_f32 v[2:3], v[76:77], v[2:3], v[100:101]
	v_cmp_ne_u32_e64 s[0:1], 1, v74
	s_cbranch_vccnz .LBB0_639
	v_bfe_u32 v74, v2, 16, 1
	v_add3_u32 v74, v2, v74, s33
	v_bfe_u32 v75, v3, 16, 1
	v_lshrrev_b32_e32 v74, 16, v74
	v_add3_u32 v75, v3, v75, s33
	v_and_or_b32 v74, v75, s11, v74
	v_bfe_u32 v75, v4, 16, 1
	v_add3_u32 v75, v4, v75, s33
	v_bfe_u32 v76, v5, 16, 1
	v_lshrrev_b32_e32 v75, 16, v75
	v_add3_u32 v76, v5, v76, s33
	v_and_or_b32 v75, v76, s11, v75
	s_mov_b64 s[4:5], 0
	flat_store_dwordx2 v[82:83], v[74:75] offset:512

; __device__ __forceinline__ unsigned pk2(float lo, float hi) { return f2bf(lo) | (f2bf(hi) << 16); }
; template <int NR>
; __device__ __forceinline__ void ln_rows(const _Float16* z, bf16* xb, float* st, float* outf, int m0, int stride, const float* g, const float* b, int lane, bool final_out) {
;     ...
;     for (int r = 0; r < NR; ++r) { const int m = m0 + r * stride; const float rstd = 1.f / sqrtf(s2[r] * (1.f / D) + LN_EPS);
;         if (!final_out && lane == 0) *(f32x2*)(st + 2 * (size_t)m) = (f32x2){mean[r], rstd};
;         f32x4* xr = (f32x4*)(outf + (size_t)m * D) + lane; unsigned long long* o8 = (unsigned long long*)(xb + (size_t)m * D) + lane;
; #pragma unroll
;         for (int j = 0; j < 4; ++j) { const f32x4 gg = ((const f32x4*)g)[lane + 64 * j], bb = ((const f32x4*)b)[lane + 64 * j];
;             const f32x4 y = v[r][j] * rstd * gg + bb;
;             if (final_out) xr[64 * j] = y;
;             else o8[64 * j] = (unsigned long long)pk2(y.x, y.y) | ((unsigned long long)pk2(y.z, y.w) << 32); } }
.LBB0_641:
	s_nop 1
	v_mov_b64_e32 v[2:3], v[124:125]
	v_mov_b64_e32 v[4:5], v[126:127]
	s_nop 0
	v_mov_b64_e32 v[74:75], v[140:141]
	v_mov_b64_e32 v[76:77], v[142:143]
	v_mov_b32_e32 v80, v84
	v_mov_b32_e32 v81, v84
	v_pk_mul_f32 v[72:73], v[72:73], v[84:85]
	v_pk_mul_f32 v[70:71], v[70:71], v[80:81]
	s_and_b64 vcc, exec, s[0:1]
	s_mov_b64 s[4:5], -1
	v_pk_fma_f32 v[4:5], v[70:71], v[4:5], v[76:77]
	v_pk_fma_f32 v[2:3], v[72:73], v[2:3], v[74:75]
	s_cbranch_vccnz .LBB0_643
	v_bfe_u32 v70, v2, 16, 1
	v_add3_u32 v70, v2, v70, s33
	v_bfe_u32 v71, v3, 16, 1
	v_lshrrev_b32_e32 v70, 16, v70
	v_add3_u32 v71, v3, v71, s33
	v_and_or_b32 v70, v71, s11, v70
	v_bfe_u32 v71, v4, 16, 1
	v_add3_u32 v71, v4, v71, s33
	v_bfe_u32 v72, v5, 16, 1
	v_lshrrev_b32_e32 v71, 16, v71
	v_add3_u32 v72, v5, v72, s33
	v_and_or_b32 v71, v72, s11, v71
	s_mov_b64 s[4:5], 0
	flat_store_dwordx2 v[82:83], v[70:71] offset:1024

; __device__ __forceinline__ unsigned pk2(float lo, float hi) { return f2bf(lo) | (f2bf(hi) << 16); }
; template <int NR>
; __device__ __forceinline__ void ln_rows(const _Float16* z, bf16* xb, float* st, float* outf, int m0, int stride, const float* g, const float* b, int lane, bool final_out) {
;     ...
;     for (int r = 0; r < NR; ++r) { const int m = m0 + r * stride; const float rstd = 1.f / sqrtf(s2[r] * (1.f / D) + LN_EPS);
;         if (!final_out && lane == 0) *(f32x2*)(st + 2 * (size_t)m) = (f32x2){mean[r], rstd};
;         f32x4* xr = (f32x4*)(outf + (size_t)m * D) + lane; unsigned long long* o8 = (unsigned long long*)(xb + (size_t)m * D) + lane;
; #pragma unroll
;         for (int j = 0; j < 4; ++j) { const f32x4 gg = ((const f32x4*)g)[lane + 64 * j], bb = ((const f32x4*)b)[lane + 64 * j];
;             const f32x4 y = v[r][j] * rstd * gg + bb;
;             if (final_out) xr[64 * j] = y;
;             else o8[64 * j] = (unsigned long long)pk2(y.x, y.y) | ((unsigned long long)pk2(y.z, y.w) << 32); } }
.LBB0_645:
	s_nop 1
	v_mov_b64_e32 v[2:3], v[128:129]
	v_mov_b64_e32 v[4:5], v[130:131]
	s_nop 0
	v_mov_b64_e32 v[70:71], v[144:145]
	v_mov_b64_e32 v[72:73], v[146:147]
	v_mov_b32_e32 v74, v84
	v_mov_b32_e32 v75, v84
	v_pk_mul_f32 v[68:69], v[68:69], v[84:85]
	v_pk_mul_f32 v[66:67], v[66:67], v[74:75]
	s_and_b64 vcc, exec, s[0:1]
	s_mov_b64 s[4:5], -1
	v_pk_fma_f32 v[4:5], v[66:67], v[4:5], v[72:73]
	v_pk_fma_f32 v[2:3], v[68:69], v[2:3], v[70:71]
	s_cbranch_vccnz .LBB0_647
	v_bfe_u32 v66, v2, 16, 1
	v_add3_u32 v66, v2, v66, s33
	v_bfe_u32 v67, v3, 16, 1
	v_lshrrev_b32_e32 v66, 16, v66
	v_add3_u32 v67, v3, v67, s33
	v_and_or_b32 v66, v67, s11, v66
	v_bfe_u32 v67, v4, 16, 1
	v_add3_u32 v67, v4, v67, s33
	v_bfe_u32 v68, v5, 16, 1
	v_lshrrev_b32_e32 v67, 16, v67
	v_add3_u32 v68, v5, v68, s33
	v_and_or_b32 v67, v68, s11, v67
	s_mov_b64 s[4:5], 0
	flat_store_dwordx2 v[82:83], v[66:67] offset:1536

; __device__ __forceinline__ unsigned pk2(float lo, float hi) { return f2bf(lo) | (f2bf(hi) << 16); }
; template <int NR>
; __device__ __forceinline__ void ln_rows(const _Float16* z, bf16* xb, float* st, float* outf, int m0, int stride, const float* g, const float* b, int lane, bool final_out) {
;     ...
;     for (int r = 0; r < NR; ++r) { const int m = m0 + r * stride; const float rstd = 1.f / sqrtf(s2[r] * (1.f / D) + LN_EPS);
;         if (!final_out && lane == 0) *(f32x2*)(st + 2 * (size_t)m) = (f32x2){mean[r], rstd};
;         f32x4* xr = (f32x4*)(outf + (size_t)m * D) + lane; unsigned long long* o8 = (unsigned long long*)(xb + (size_t)m * D) + lane;
; #pragma unroll
;         for (int j = 0; j < 4; ++j) { const f32x4 gg = ((const f32x4*)g)[lane + 64 * j], bb = ((const f32x4*)b)[lane + 64 * j];
;             const f32x4 y = v[r][j] * rstd * gg + bb;
;             if (final_out) xr[64 * j] = y;
;             else o8[64 * j] = (unsigned long long)pk2(y.x, y.y) | ((unsigned long long)pk2(y.z, y.w) << 32); } }
.LBB0_651:
	s_or_b64 exec, exec, s[4:5]
	s_nop 1
	v_mov_b64_e32 v[2:3], v[116:117]
	v_mov_b64_e32 v[4:5], v[118:119]
	v_mov_b64_e32 v[70:71], v[132:133]
	v_mov_b64_e32 v[72:73], v[134:135]
	v_pk_mul_f32 v[62:63], v[62:63], v[68:69] op_sel_hi:[1,0]
	v_pk_mul_f32 v[64:65], v[64:65], v[68:69] op_sel_hi:[1,0]
	v_lshl_add_u64 v[66:67], v[10:11], 0, s[52:53]
	s_and_b64 vcc, exec, s[0:1]
	s_mov_b64 s[4:5], -1
	v_pk_fma_f32 v[4:5], v[62:63], v[4:5], v[72:73]
	v_pk_fma_f32 v[2:3], v[64:65], v[2:3], v[70:71]
	s_cbranch_vccnz .LBB0_653
	v_bfe_u32 v62, v2, 16, 1
	v_add3_u32 v62, v2, v62, s33
	v_bfe_u32 v63, v3, 16, 1
	v_lshrrev_b32_e32 v62, 16, v62
	v_add3_u32 v63, v3, v63, s33
	v_and_or_b32 v62, v63, s11, v62
	v_bfe_u32 v63, v4, 16, 1
	v_add3_u32 v63, v4, v63, s33
	v_bfe_u32 v64, v5, 16, 1
	v_lshrrev_b32_e32 v63, 16, v63
	v_add3_u32 v64, v5, v64, s33
	v_and_or_b32 v63, v64, s11, v63
	s_mov_b64 s[4:5], 0
	flat_store_dwordx2 v[66:67], v[62:63]

; __device__ __forceinline__ unsigned pk2(float lo, float hi) { return f2bf(lo) | (f2bf(hi) << 16); }
; template <int NR>
; __device__ __forceinline__ void ln_rows(const _Float16* z, bf16* xb, float* st, float* outf, int m0, int stride, const float* g, const float* b, int lane, bool final_out) {
;     ...
;     for (int r = 0; r < NR; ++r) { const int m = m0 + r * stride; const float rstd = 1.f / sqrtf(s2[r] * (1.f / D) + LN_EPS);
;         if (!final_out && lane == 0) *(f32x2*)(st + 2 * (size_t)m) = (f32x2){mean[r], rstd};
;         f32x4* xr = (f32x4*)(outf + (size_t)m * D) + lane; unsigned long long* o8 = (unsigned long long*)(xb + (size_t)m * D) + lane;
; #pragma unroll
;         for (int j = 0; j < 4; ++j) { const f32x4 gg = ((const f32x4*)g)[lane + 64 * j], bb = ((const f32x4*)b)[lane + 64 * j];
;             const f32x4 y = v[r][j] * rstd * gg + bb;
;             if (final_out) xr[64 * j] = y;
;             else o8[64 * j] = (unsigned long long)pk2(y.x, y.y) | ((unsigned long long)pk2(y.z, y.w) << 32); } }
.LBB0_655:
	s_nop 1
	v_mov_b64_e32 v[2:3], v[120:121]
	v_mov_b64_e32 v[4:5], v[122:123]
	s_nop 0
	v_mov_b64_e32 v[70:71], v[136:137]
	v_mov_b64_e32 v[72:73], v[138:139]
	v_mov_b32_e32 v69, v68
	v_mov_b32_e32 v64, v68
	v_mov_b32_e32 v65, v68
	v_pk_mul_f32 v[58:59], v[58:59], v[64:65]
	v_pk_mul_f32 v[60:61], v[60:61], v[68:69]
	s_and_b64 vcc, exec, s[0:1]
	s_mov_b64 s[4:5], -1
	v_pk_fma_f32 v[4:5], v[58:59], v[4:5], v[72:73]
	v_pk_fma_f32 v[2:3], v[60:61], v[2:3], v[70:71]
	s_cbranch_vccnz .LBB0_657
	v_bfe_u32 v58, v2, 16, 1
	v_add3_u32 v58, v2, v58, s33
	v_bfe_u32 v59, v3, 16, 1
	v_lshrrev_b32_e32 v58, 16, v58
	v_add3_u32 v59, v3, v59, s33
	v_and_or_b32 v58, v59, s11, v58
	v_bfe_u32 v59, v4, 16, 1
	v_add3_u32 v59, v4, v59, s33
	v_bfe_u32 v60, v5, 16, 1
	v_lshrrev_b32_e32 v59, 16, v59
	v_add3_u32 v60, v5, v60, s33
	v_and_or_b32 v59, v60, s11, v59
	s_mov_b64 s[4:5], 0
	flat_store_dwordx2 v[66:67], v[58:59] offset:512

; __device__ __forceinline__ unsigned pk2(float lo, float hi) { return f2bf(lo) | (f2bf(hi) << 16); }
; template <int NR>
; __device__ __forceinline__ void ln_rows(const _Float16* z, bf16* xb, float* st, float* outf, int m0, int stride, const float* g, const float* b, int lane, bool final_out) {
;     ...
;     for (int r = 0; r < NR; ++r) { const int m = m0 + r * stride; const float rstd = 1.f / sqrtf(s2[r] * (1.f / D) + LN_EPS);
;         if (!final_out && lane == 0) *(f32x2*)(st + 2 * (size_t)m) = (f32x2){mean[r], rstd};
;         f32x4* xr = (f32x4*)(outf + (size_t)m * D) + lane; unsigned long long* o8 = (unsigned long long*)(xb + (size_t)m * D) + lane;
; #pragma unroll
;         for (int j = 0; j < 4; ++j) { const f32x4 gg = ((const f32x4*)g)[lane + 64 * j], bb = ((const f32x4*)b)[lane + 64 * j];
;             const f32x4 y = v[r][j] * rstd * gg + bb;
;             if (final_out) xr[64 * j] = y;
;             else o8[64 * j] = (unsigned long long)pk2(y.x, y.y) | ((unsigned long long)pk2(y.z, y.w) << 32); } }
.LBB0_659:
	s_nop 1
	v_mov_b64_e32 v[2:3], v[124:125]
	v_mov_b64_e32 v[4:5], v[126:127]
	s_nop 0
	v_mov_b64_e32 v[58:59], v[140:141]
	v_mov_b64_e32 v[60:61], v[142:143]
	v_mov_b32_e32 v64, v68
	v_mov_b32_e32 v65, v68
	v_pk_mul_f32 v[56:57], v[56:57], v[68:69]
	v_pk_mul_f32 v[54:55], v[54:55], v[64:65]
	s_and_b64 vcc, exec, s[0:1]
	s_mov_b64 s[4:5], -1
	v_pk_fma_f32 v[4:5], v[54:55], v[4:5], v[60:61]
	v_pk_fma_f32 v[2:3], v[56:57], v[2:3], v[58:59]
	s_cbranch_vccnz .LBB0_661
	v_bfe_u32 v54, v2, 16, 1
	v_add3_u32 v54, v2, v54, s33
	v_bfe_u32 v55, v3, 16, 1
	v_lshrrev_b32_e32 v54, 16, v54
	v_add3_u32 v55, v3, v55, s33
	v_and_or_b32 v54, v55, s11, v54
	v_bfe_u32 v55, v4, 16, 1
	v_add3_u32 v55, v4, v55, s33
	v_bfe_u32 v56, v5, 16, 1
	v_lshrrev_b32_e32 v55, 16, v55
	v_add3_u32 v56, v5, v56, s33
	v_and_or_b32 v55, v56, s11, v55
	s_mov_b64 s[4:5], 0
	flat_store_dwordx2 v[66:67], v[54:55] offset:1024

; __device__ __forceinline__ unsigned pk2(float lo, float hi) { return f2bf(lo) | (f2bf(hi) << 16); }
; template <int NR>
; __device__ __forceinline__ void ln_rows(const _Float16* z, bf16* xb, float* st, float* outf, int m0, int stride, const float* g, const float* b, int lane, bool final_out) {
;     ...
;     for (int r = 0; r < NR; ++r) { const int m = m0 + r * stride; const float rstd = 1.f / sqrtf(s2[r] * (1.f / D) + LN_EPS);
;         if (!final_out && lane == 0) *(f32x2*)(st + 2 * (size_t)m) = (f32x2){mean[r], rstd};
;         f32x4* xr = (f32x4*)(outf + (size_t)m * D) + lane; unsigned long long* o8 = (unsigned long long*)(xb + (size_t)m * D) + lane;
; #pragma unroll
;         for (int j = 0; j < 4; ++j) { const f32x4 gg = ((const f32x4*)g)[lane + 64 * j], bb = ((const f32x4*)b)[lane + 64 * j];
;             const f32x4 y = v[r][j] * rstd * gg + bb;
;             if (final_out) xr[64 * j] = y;
;             else o8[64 * j] = (unsigned long long)pk2(y.x, y.y) | ((unsigned long long)pk2(y.z, y.w) << 32); } }
.LBB0_663:
	s_nop 1
	v_mov_b64_e32 v[2:3], v[128:129]
	v_mov_b64_e32 v[4:5], v[130:131]
	s_nop 0
	v_mov_b64_e32 v[54:55], v[144:145]
	v_mov_b64_e32 v[56:57], v[146:147]
	v_mov_b32_e32 v58, v68
	v_mov_b32_e32 v59, v68
	v_pk_mul_f32 v[52:53], v[52:53], v[68:69]
	v_pk_mul_f32 v[50:51], v[50:51], v[58:59]
	s_and_b64 vcc, exec, s[0:1]
	s_mov_b64 s[4:5], -1
	v_pk_fma_f32 v[4:5], v[50:51], v[4:5], v[56:57]
	v_pk_fma_f32 v[2:3], v[52:53], v[2:3], v[54:55]
	s_cbranch_vccnz .LBB0_665
	v_bfe_u32 v50, v2, 16, 1
	v_add3_u32 v50, v2, v50, s33
	v_bfe_u32 v51, v3, 16, 1
	v_lshrrev_b32_e32 v50, 16, v50
	v_add3_u32 v51, v3, v51, s33
	v_and_or_b32 v50, v51, s11, v50
	v_bfe_u32 v51, v4, 16, 1
	v_add3_u32 v51, v4, v51, s33
	v_bfe_u32 v52, v5, 16, 1
	v_lshrrev_b32_e32 v51, 16, v51
	v_add3_u32 v52, v5, v52, s33
	v_and_or_b32 v51, v52, s11, v51
	s_mov_b64 s[4:5], 0
	flat_store_dwordx2 v[66:67], v[50:51] offset:1536

; __device__ __forceinline__ unsigned pk2(float lo, float hi) { return f2bf(lo) | (f2bf(hi) << 16); }
; template <int NR>
; __device__ __forceinline__ void ln_rows(const _Float16* z, bf16* xb, float* st, float* outf, int m0, int stride, const float* g, const float* b, int lane, bool final_out) {
;     ...
;     for (int r = 0; r < NR; ++r) { const int m = m0 + r * stride; const float rstd = 1.f / sqrtf(s2[r] * (1.f / D) + LN_EPS);
;         if (!final_out && lane == 0) *(f32x2*)(st + 2 * (size_t)m) = (f32x2){mean[r], rstd};
;         f32x4* xr = (f32x4*)(outf + (size_t)m * D) + lane; unsigned long long* o8 = (unsigned long long*)(xb + (size_t)m * D) + lane;
; #pragma unroll
;         for (int j = 0; j < 4; ++j) { const f32x4 gg = ((const f32x4*)g)[lane + 64 * j], bb = ((const f32x4*)b)[lane + 64 * j];
;             const f32x4 y = v[r][j] * rstd * gg + bb;
;             if (final_out) xr[64 * j] = y;
;             else o8[64 * j] = (unsigned long long)pk2(y.x, y.y) | ((unsigned long long)pk2(y.z, y.w) << 32); } }
.LBB0_669:
	s_or_b64 exec, exec, s[4:5]
	s_nop 1
	v_mov_b64_e32 v[2:3], v[116:117]
	v_mov_b64_e32 v[4:5], v[118:119]
	v_mov_b64_e32 v[54:55], v[132:133]
	v_mov_b64_e32 v[56:57], v[134:135]
	v_pk_mul_f32 v[46:47], v[46:47], v[52:53] op_sel_hi:[1,0]
	v_pk_mul_f32 v[48:49], v[48:49], v[52:53] op_sel_hi:[1,0]
	v_lshl_add_u64 v[50:51], v[10:11], 0, s[50:51]
	s_and_b64 vcc, exec, s[0:1]
	s_mov_b64 s[4:5], -1
	v_pk_fma_f32 v[4:5], v[46:47], v[4:5], v[56:57]
	v_pk_fma_f32 v[2:3], v[48:49], v[2:3], v[54:55]
	s_cbranch_vccnz .LBB0_671
	v_bfe_u32 v46, v2, 16, 1
	v_add3_u32 v46, v2, v46, s33
	v_bfe_u32 v47, v3, 16, 1
	v_lshrrev_b32_e32 v46, 16, v46
	v_add3_u32 v47, v3, v47, s33
	v_and_or_b32 v46, v47, s11, v46
	v_bfe_u32 v47, v4, 16, 1
	v_add3_u32 v47, v4, v47, s33
	v_bfe_u32 v48, v5, 16, 1
	v_lshrrev_b32_e32 v47, 16, v47
	v_add3_u32 v48, v5, v48, s33
	v_and_or_b32 v47, v48, s11, v47
	s_mov_b64 s[4:5], 0
	flat_store_dwordx2 v[50:51], v[46:47]

; __device__ __forceinline__ unsigned pk2(float lo, float hi) { return f2bf(lo) | (f2bf(hi) << 16); }
; template <int NR>
; __device__ __forceinline__ void ln_rows(const _Float16* z, bf16* xb, float* st, float* outf, int m0, int stride, const float* g, const float* b, int lane, bool final_out) {
;     ...
;     for (int r = 0; r < NR; ++r) { const int m = m0 + r * stride; const float rstd = 1.f / sqrtf(s2[r] * (1.f / D) + LN_EPS);
;         if (!final_out && lane == 0) *(f32x2*)(st + 2 * (size_t)m) = (f32x2){mean[r], rstd};
;         f32x4* xr = (f32x4*)(outf + (size_t)m * D) + lane; unsigned long long* o8 = (unsigned long long*)(xb + (size_t)m * D) + lane;
; #pragma unroll
;         for (int j = 0; j < 4; ++j) { const f32x4 gg = ((const f32x4*)g)[lane + 64 * j], bb = ((const f32x4*)b)[lane + 64 * j];
;             const f32x4 y = v[r][j] * rstd * gg + bb;
;             if (final_out) xr[64 * j] = y;
;             else o8[64 * j] = (unsigned long long)pk2(y.x, y.y) | ((unsigned long long)pk2(y.z, y.w) << 32); } }
.LBB0_673:
	s_nop 1
	v_mov_b64_e32 v[2:3], v[120:121]
	v_mov_b64_e32 v[4:5], v[122:123]
	s_nop 0
	v_mov_b64_e32 v[54:55], v[136:137]
	v_mov_b64_e32 v[56:57], v[138:139]
	v_mov_b32_e32 v53, v52
	v_mov_b32_e32 v48, v52
	v_mov_b32_e32 v49, v52
	v_pk_mul_f32 v[42:43], v[42:43], v[48:49]
	v_pk_mul_f32 v[44:45], v[44:45], v[52:53]
	s_and_b64 vcc, exec, s[0:1]
	s_mov_b64 s[4:5], -1
	v_pk_fma_f32 v[4:5], v[42:43], v[4:5], v[56:57]
	v_pk_fma_f32 v[2:3], v[44:45], v[2:3], v[54:55]
	s_cbranch_vccnz .LBB0_675
	v_bfe_u32 v42, v2, 16, 1
	v_add3_u32 v42, v2, v42, s33
	v_bfe_u32 v43, v3, 16, 1
	v_lshrrev_b32_e32 v42, 16, v42
	v_add3_u32 v43, v3, v43, s33
	v_and_or_b32 v42, v43, s11, v42
	v_bfe_u32 v43, v4, 16, 1
	v_add3_u32 v43, v4, v43, s33
	v_bfe_u32 v44, v5, 16, 1
	v_lshrrev_b32_e32 v43, 16, v43
	v_add3_u32 v44, v5, v44, s33
	v_and_or_b32 v43, v44, s11, v43
	s_mov_b64 s[4:5], 0
	flat_store_dwordx2 v[50:51], v[42:43] offset:512

; __device__ __forceinline__ unsigned pk2(float lo, float hi) { return f2bf(lo) | (f2bf(hi) << 16); }
; template <int NR>
; __device__ __forceinline__ void ln_rows(const _Float16* z, bf16* xb, float* st, float* outf, int m0, int stride, const float* g, const float* b, int lane, bool final_out) {
;     ...
;     for (int r = 0; r < NR; ++r) { const int m = m0 + r * stride; const float rstd = 1.f / sqrtf(s2[r] * (1.f / D) + LN_EPS);
;         if (!final_out && lane == 0) *(f32x2*)(st + 2 * (size_t)m) = (f32x2){mean[r], rstd};
;         f32x4* xr = (f32x4*)(outf + (size_t)m * D) + lane; unsigned long long* o8 = (unsigned long long*)(xb + (size_t)m * D) + lane;
; #pragma unroll
;         for (int j = 0; j < 4; ++j) { const f32x4 gg = ((const f32x4*)g)[lane + 64 * j], bb = ((const f32x4*)b)[lane + 64 * j];
;             const f32x4 y = v[r][j] * rstd * gg + bb;
;             if (final_out) xr[64 * j] = y;
;             else o8[64 * j] = (unsigned long long)pk2(y.x, y.y) | ((unsigned long long)pk2(y.z, y.w) << 32); } }
.LBB0_677:
	s_nop 1
	v_mov_b64_e32 v[2:3], v[124:125]
	v_mov_b64_e32 v[4:5], v[126:127]
	s_nop 0
	v_mov_b64_e32 v[42:43], v[140:141]
	v_mov_b64_e32 v[44:45], v[142:143]
	v_mov_b32_e32 v48, v52
	v_mov_b32_e32 v49, v52
	v_pk_mul_f32 v[40:41], v[40:41], v[52:53]
	v_pk_mul_f32 v[38:39], v[38:39], v[48:49]
	s_and_b64 vcc, exec, s[0:1]
	s_mov_b64 s[4:5], -1
	v_pk_fma_f32 v[4:5], v[38:39], v[4:5], v[44:45]
	v_pk_fma_f32 v[2:3], v[40:41], v[2:3], v[42:43]
	s_cbranch_vccnz .LBB0_679
	v_bfe_u32 v38, v2, 16, 1
	v_add3_u32 v38, v2, v38, s33
	v_bfe_u32 v39, v3, 16, 1
	v_lshrrev_b32_e32 v38, 16, v38
	v_add3_u32 v39, v3, v39, s33
	v_and_or_b32 v38, v39, s11, v38
	v_bfe_u32 v39, v4, 16, 1
	v_add3_u32 v39, v4, v39, s33
	v_bfe_u32 v40, v5, 16, 1
	v_lshrrev_b32_e32 v39, 16, v39
	v_add3_u32 v40, v5, v40, s33
	v_and_or_b32 v39, v40, s11, v39
	s_mov_b64 s[4:5], 0
	flat_store_dwordx2 v[50:51], v[38:39] offset:1024

; __device__ __forceinline__ unsigned pk2(float lo, float hi) { return f2bf(lo) | (f2bf(hi) << 16); }
; template <int NR>
; __device__ __forceinline__ void ln_rows(const _Float16* z, bf16* xb, float* st, float* outf, int m0, int stride, const float* g, const float* b, int lane, bool final_out) {
;     ...
;     for (int r = 0; r < NR; ++r) { const int m = m0 + r * stride; const float rstd = 1.f / sqrtf(s2[r] * (1.f / D) + LN_EPS);
;         if (!final_out && lane == 0) *(f32x2*)(st + 2 * (size_t)m) = (f32x2){mean[r], rstd};
;         f32x4* xr = (f32x4*)(outf + (size_t)m * D) + lane; unsigned long long* o8 = (unsigned long long*)(xb + (size_t)m * D) + lane;
; #pragma unroll
;         for (int j = 0; j < 4; ++j) { const f32x4 gg = ((const f32x4*)g)[lane + 64 * j], bb = ((const f32x4*)b)[lane + 64 * j];
;             const f32x4 y = v[r][j] * rstd * gg + bb;
;             if (final_out) xr[64 * j] = y;
;             else o8[64 * j] = (unsigned long long)pk2(y.x, y.y) | ((unsigned long long)pk2(y.z, y.w) << 32); } }
.LBB0_681:
	s_nop 1
	v_mov_b64_e32 v[2:3], v[128:129]
	v_mov_b64_e32 v[4:5], v[130:131]
	s_nop 0
	v_mov_b64_e32 v[38:39], v[144:145]
	v_mov_b64_e32 v[40:41], v[146:147]
	v_mov_b32_e32 v42, v52
	v_mov_b32_e32 v43, v52
	v_pk_mul_f32 v[36:37], v[36:37], v[52:53]
	v_pk_mul_f32 v[34:35], v[34:35], v[42:43]
	s_and_b64 vcc, exec, s[0:1]
	s_mov_b64 s[4:5], -1
	v_pk_fma_f32 v[4:5], v[34:35], v[4:5], v[40:41]
	v_pk_fma_f32 v[2:3], v[36:37], v[2:3], v[38:39]
	s_cbranch_vccnz .LBB0_683
	v_bfe_u32 v34, v2, 16, 1
	v_add3_u32 v34, v2, v34, s33
	v_bfe_u32 v35, v3, 16, 1
	v_lshrrev_b32_e32 v34, 16, v34
	v_add3_u32 v35, v3, v35, s33
	v_and_or_b32 v34, v35, s11, v34
	v_bfe_u32 v35, v4, 16, 1
	v_add3_u32 v35, v4, v35, s33
	v_bfe_u32 v36, v5, 16, 1
	v_lshrrev_b32_e32 v35, 16, v35
	v_add3_u32 v36, v5, v36, s33
	v_and_or_b32 v35, v36, s11, v35
	s_mov_b64 s[4:5], 0
	flat_store_dwordx2 v[50:51], v[34:35] offset:1536

; __device__ __forceinline__ unsigned pk2(float lo, float hi) { return f2bf(lo) | (f2bf(hi) << 16); }
; template <int NR>
; __device__ __forceinline__ void ln_rows(const _Float16* z, bf16* xb, float* st, float* outf, int m0, int stride, const float* g, const float* b, int lane, bool final_out) {
;     ...
;     for (int r = 0; r < NR; ++r) { const int m = m0 + r * stride; const float rstd = 1.f / sqrtf(s2[r] * (1.f / D) + LN_EPS);
;         if (!final_out && lane == 0) *(f32x2*)(st + 2 * (size_t)m) = (f32x2){mean[r], rstd};
;         f32x4* xr = (f32x4*)(outf + (size_t)m * D) + lane; unsigned long long* o8 = (unsigned long long*)(xb + (size_t)m * D) + lane;
; #pragma unroll
;         for (int j = 0; j < 4; ++j) { const f32x4 gg = ((const f32x4*)g)[lane + 64 * j], bb = ((const f32x4*)b)[lane + 64 * j];
;             const f32x4 y = v[r][j] * rstd * gg + bb;
;             if (final_out) xr[64 * j] = y;
;             else o8[64 * j] = (unsigned long long)pk2(y.x, y.y) | ((unsigned long long)pk2(y.z, y.w) << 32); } }
.LBB0_687:
	s_or_b64 exec, exec, s[4:5]
	s_nop 1
	v_mov_b64_e32 v[2:3], v[116:117]
	v_mov_b64_e32 v[4:5], v[118:119]
	v_mov_b64_e32 v[38:39], v[132:133]
	v_mov_b64_e32 v[40:41], v[134:135]
	v_pk_mul_f32 v[30:31], v[30:31], v[36:37] op_sel_hi:[1,0]
	v_pk_mul_f32 v[32:33], v[32:33], v[36:37] op_sel_hi:[1,0]
	v_lshl_add_u64 v[34:35], v[10:11], 0, s[46:47]
	s_and_b64 vcc, exec, s[0:1]
	s_mov_b64 s[4:5], -1
	v_pk_fma_f32 v[4:5], v[30:31], v[4:5], v[40:41]
	v_pk_fma_f32 v[2:3], v[32:33], v[2:3], v[38:39]
	s_cbranch_vccnz .LBB0_689
	v_bfe_u32 v7, v2, 16, 1
	v_add3_u32 v7, v2, v7, s33
	v_bfe_u32 v30, v3, 16, 1
	v_lshrrev_b32_e32 v7, 16, v7
	v_add3_u32 v30, v3, v30, s33
	v_and_or_b32 v30, v30, s11, v7
	v_bfe_u32 v7, v4, 16, 1
	v_add3_u32 v7, v4, v7, s33
	v_bfe_u32 v31, v5, 16, 1
	v_lshrrev_b32_e32 v7, 16, v7
	v_add3_u32 v31, v5, v31, s33
	v_and_or_b32 v31, v31, s11, v7
	s_mov_b64 s[4:5], 0
	flat_store_dwordx2 v[34:35], v[30:31]

; __device__ __forceinline__ unsigned pk2(float lo, float hi) { return f2bf(lo) | (f2bf(hi) << 16); }
; template <int NR>
; __device__ __forceinline__ void ln_rows(const _Float16* z, bf16* xb, float* st, float* outf, int m0, int stride, const float* g, const float* b, int lane, bool final_out) {
;     ...
;     for (int r = 0; r < NR; ++r) { const int m = m0 + r * stride; const float rstd = 1.f / sqrtf(s2[r] * (1.f / D) + LN_EPS);
;         if (!final_out && lane == 0) *(f32x2*)(st + 2 * (size_t)m) = (f32x2){mean[r], rstd};
;         f32x4* xr = (f32x4*)(outf + (size_t)m * D) + lane; unsigned long long* o8 = (unsigned long long*)(xb + (size_t)m * D) + lane;
; #pragma unroll
;         for (int j = 0; j < 4; ++j) { const f32x4 gg = ((const f32x4*)g)[lane + 64 * j], bb = ((const f32x4*)b)[lane + 64 * j];
;             const f32x4 y = v[r][j] * rstd * gg + bb;
;             if (final_out) xr[64 * j] = y;
;             else o8[64 * j] = (unsigned long long)pk2(y.x, y.y) | ((unsigned long long)pk2(y.z, y.w) << 32); } }
.LBB0_691:
	s_nop 1
	v_mov_b64_e32 v[2:3], v[120:121]
	v_mov_b64_e32 v[4:5], v[122:123]
	s_nop 0
	v_mov_b64_e32 v[38:39], v[136:137]
	v_mov_b64_e32 v[40:41], v[138:139]
	v_mov_b32_e32 v37, v36
	v_mov_b32_e32 v32, v36
	v_mov_b32_e32 v33, v36
	v_pk_mul_f32 v[26:27], v[26:27], v[32:33]
	v_pk_mul_f32 v[28:29], v[28:29], v[36:37]
	s_and_b64 vcc, exec, s[0:1]
	s_mov_b64 s[4:5], -1
	v_pk_fma_f32 v[4:5], v[26:27], v[4:5], v[40:41]
	v_pk_fma_f32 v[2:3], v[28:29], v[2:3], v[38:39]
	s_cbranch_vccnz .LBB0_693
	v_bfe_u32 v7, v2, 16, 1
	v_add3_u32 v7, v2, v7, s33
	v_bfe_u32 v26, v3, 16, 1
	v_lshrrev_b32_e32 v7, 16, v7
	v_add3_u32 v26, v3, v26, s33
	v_and_or_b32 v26, v26, s11, v7
	v_bfe_u32 v7, v4, 16, 1
	v_add3_u32 v7, v4, v7, s33
	v_bfe_u32 v27, v5, 16, 1
	v_lshrrev_b32_e32 v7, 16, v7
	v_add3_u32 v27, v5, v27, s33
	v_and_or_b32 v27, v27, s11, v7
	s_mov_b64 s[4:5], 0
	flat_store_dwordx2 v[34:35], v[26:27] offset:512

; __device__ __forceinline__ unsigned pk2(float lo, float hi) { return f2bf(lo) | (f2bf(hi) << 16); }
; template <int NR>
; __device__ __forceinline__ void ln_rows(const _Float16* z, bf16* xb, float* st, float* outf, int m0, int stride, const float* g, const float* b, int lane, bool final_out) {
;     ...
;     for (int r = 0; r < NR; ++r) { const int m = m0 + r * stride; const float rstd = 1.f / sqrtf(s2[r] * (1.f / D) + LN_EPS);
;         if (!final_out && lane == 0) *(f32x2*)(st + 2 * (size_t)m) = (f32x2){mean[r], rstd};
;         f32x4* xr = (f32x4*)(outf + (size_t)m * D) + lane; unsigned long long* o8 = (unsigned long long*)(xb + (size_t)m * D) + lane;
; #pragma unroll
;         for (int j = 0; j < 4; ++j) { const f32x4 gg = ((const f32x4*)g)[lane + 64 * j], bb = ((const f32x4*)b)[lane + 64 * j];
;             const f32x4 y = v[r][j] * rstd * gg + bb;
;             if (final_out) xr[64 * j] = y;
;             else o8[64 * j] = (unsigned long long)pk2(y.x, y.y) | ((unsigned long long)pk2(y.z, y.w) << 32); } }
.LBB0_695:
	s_nop 1
	v_mov_b64_e32 v[2:3], v[124:125]
	v_mov_b64_e32 v[4:5], v[126:127]
	s_nop 0
	v_mov_b64_e32 v[26:27], v[140:141]
	v_mov_b64_e32 v[28:29], v[142:143]
	v_mov_b32_e32 v32, v36
	v_mov_b32_e32 v33, v36
	v_pk_mul_f32 v[24:25], v[24:25], v[36:37]
	v_pk_mul_f32 v[22:23], v[22:23], v[32:33]
	s_and_b64 vcc, exec, s[0:1]
	s_mov_b64 s[4:5], -1
	v_pk_fma_f32 v[4:5], v[22:23], v[4:5], v[28:29]
	v_pk_fma_f32 v[2:3], v[24:25], v[2:3], v[26:27]
	s_cbranch_vccnz .LBB0_697
	v_bfe_u32 v7, v2, 16, 1
	v_add3_u32 v7, v2, v7, s33
	v_bfe_u32 v22, v3, 16, 1
	v_lshrrev_b32_e32 v7, 16, v7
	v_add3_u32 v22, v3, v22, s33
	v_and_or_b32 v22, v22, s11, v7
	v_bfe_u32 v7, v4, 16, 1
	v_add3_u32 v7, v4, v7, s33
	v_bfe_u32 v23, v5, 16, 1
	v_lshrrev_b32_e32 v7, 16, v7
	v_add3_u32 v23, v5, v23, s33
	v_and_or_b32 v23, v23, s11, v7
	s_mov_b64 s[4:5], 0
	flat_store_dwordx2 v[34:35], v[22:23] offset:1024

; __device__ __forceinline__ unsigned pk2(float lo, float hi) { return f2bf(lo) | (f2bf(hi) << 16); }
; template <int NR>
; __device__ __forceinline__ void ln_rows(const _Float16* z, bf16* xb, float* st, float* outf, int m0, int stride, const float* g, const float* b, int lane, bool final_out) {
;     ...
;     for (int r = 0; r < NR; ++r) { const int m = m0 + r * stride; const float rstd = 1.f / sqrtf(s2[r] * (1.f / D) + LN_EPS);
;         if (!final_out && lane == 0) *(f32x2*)(st + 2 * (size_t)m) = (f32x2){mean[r], rstd};
;         f32x4* xr = (f32x4*)(outf + (size_t)m * D) + lane; unsigned long long* o8 = (unsigned long long*)(xb + (size_t)m * D) + lane;
; #pragma unroll
;         for (int j = 0; j < 4; ++j) { const f32x4 gg = ((const f32x4*)g)[lane + 64 * j], bb = ((const f32x4*)b)[lane + 64 * j];
;             const f32x4 y = v[r][j] * rstd * gg + bb;
;             if (final_out) xr[64 * j] = y;
;             else o8[64 * j] = (unsigned long long)pk2(y.x, y.y) | ((unsigned long long)pk2(y.z, y.w) << 32); } }
.LBB0_699:
	s_nop 1
	v_mov_b64_e32 v[2:3], v[128:129]
	v_mov_b64_e32 v[4:5], v[130:131]
	s_nop 0
	v_mov_b64_e32 v[22:23], v[144:145]
	v_mov_b64_e32 v[24:25], v[146:147]
	v_mov_b32_e32 v26, v36
	v_mov_b32_e32 v27, v36
	v_pk_mul_f32 v[20:21], v[20:21], v[36:37]
	v_pk_mul_f32 v[18:19], v[18:19], v[26:27]
	s_and_b64 vcc, exec, s[0:1]
	s_mov_b64 s[0:1], -1
	v_pk_fma_f32 v[4:5], v[18:19], v[4:5], v[24:25]
	v_pk_fma_f32 v[2:3], v[20:21], v[2:3], v[22:23]
	s_cbranch_vccnz .LBB0_701
	v_bfe_u32 v7, v2, 16, 1
	v_add3_u32 v7, v2, v7, s33
	v_bfe_u32 v18, v3, 16, 1
	v_lshrrev_b32_e32 v7, 16, v7
	v_add3_u32 v18, v3, v18, s33
	v_and_or_b32 v18, v18, s11, v7
	v_bfe_u32 v7, v4, 16, 1
	v_add3_u32 v7, v4, v7, s33
	v_bfe_u32 v19, v5, 16, 1
	v_lshrrev_b32_e32 v7, 16, v7
	v_add3_u32 v19, v5, v19, s33
	v_and_or_b32 v19, v19, s11, v7
	s_mov_b64 s[0:1], 0
	flat_store_dwordx2 v[34:35], v[18:19] offset:1536
